# post phase gated-deltanet part: three heads loaded together per trip, s5 copy loads batched
# speedup vs baseline: 1.4509x; 1.0095x over previous
; __device__ __forceinline__ f32x4 unpk4(u32x2 v) { return (f32x4){bflo(v.x), bfhi(v.x), bflo(v.y), bfhi(v.y)}; }
; __device__ __forceinline__ u32x2 pk4(f32x4 v) { u32x2 r; r.x = pk2(v[0], v[1]); r.y = pk2(v[2], v[3]); return r; }
; __device__ __forceinline__ float siluf_(float x) { return x * rcpf_(1.f + __expf(-x)); }
; __device__ __forceinline__ void phase_post(const PP& p, int l) {
;     ...
; #pragma unroll 1
;         for (int tg = 0; tg < 4; ++tg) {
;             const int row = item * 16 + tg * 4 + tk, b = row / TT, j = row - b * TT;
;             const f32x4 gn = *(const f32x4*)(p.in[I_GNG] + l * 64 + 4 * c4);
; #pragma unroll 3
;             for (int h = 0; h < 6; ++h) {
;                 const int c = h * 64 + 4 * c4;
;                 const f32x4 o = unpk4(*(const u32x2*)(YO + 2 * YS + (size_t)row * 384 + c)) + unpk4(*(const u32x2*)(YO + 3 * YS + (size_t)row * 384 + c));
;                 const float rs = __builtin_amdgcn_rsqf(red16(o[0] * o[0] + o[1] * o[1] + o[2] * o[2] + o[3] * o[3]) * (1.f / 64.f) + 1e-6f);
;                 f32x4 gt = unpk4(*(const u32x2*)(Z + (size_t)row * ZLD + 2584 + c));
; #pragma unroll
;                 for (int i = 0; i < 4; ++i) gt[i] = siluf_(gt[i]);
;                 *(u32x2*)(MIX + (size_t)row * DM + 384 + c) = pk4(o * rs * gn * gt);
;             }
.LBB0_1013:
	v_lshl_add_u64 v[36:37], v[12:13], 0, s[26:27]
	v_add_co_u32_e32 v42, vcc, 0x16a3c000, v36
	s_mov_b32 s7, 0x7971000
	s_nop 0
	v_addc_co_u32_e32 v43, vcc, 0, v37, vcc
	v_add_co_u32_e32 v38, vcc, 0x182fc000, v36
	s_nop 1
	v_addc_co_u32_e32 v39, vcc, 0, v37, vcc
	v_lshl_add_u64 v[36:37], v[10:11], 0, s[26:27]
	v_add_co_u32_e32 v36, vcc, s7, v36
	s_nop 1
	v_addc_co_u32_e32 v37, vcc, 0, v37, vcc
	global_load_dwordx2 v[84:85], v[42:43], off
	global_load_dwordx2 v[86:87], v[38:39], off
	global_load_dwordx2 v[88:89], v[36:37], off offset:1072
	global_load_dwordx2 v[182:183], v[42:43], off offset:128
	global_load_dwordx2 v[184:185], v[38:39], off offset:128
	global_load_dwordx2 v[186:187], v[36:37], off offset:1200
	global_load_dwordx2 v[212:213], v[42:43], off offset:256
	global_load_dwordx2 v[214:215], v[38:39], off offset:256
	global_load_dwordx2 v[216:217], v[36:37], off offset:1328
	v_lshl_add_u64 v[40:41], v[8:9], 0, s[26:27]
	v_add_co_u32_e32 v40, vcc, s17, v40
	s_add_u32 s26, s26, 0x180
	s_addc_u32 s27, s27, 0
	v_addc_co_u32_e32 v41, vcc, 0, v41, vcc
	s_waitcnt vmcnt(0)
	v_lshlrev_b32_e32 v90, 16, v84
	v_lshlrev_b32_e32 v188, 16, v182
	v_lshlrev_b32_e32 v218, 16, v212
	v_and_b32_e32 v91, 0xffff0000, v84
	v_and_b32_e32 v189, 0xffff0000, v182
	v_and_b32_e32 v219, 0xffff0000, v212
	v_lshlrev_b32_e32 v92, 16, v85
	v_lshlrev_b32_e32 v190, 16, v183
	v_lshlrev_b32_e32 v220, 16, v213
	v_and_b32_e32 v93, 0xffff0000, v85
	v_and_b32_e32 v191, 0xffff0000, v183
	v_and_b32_e32 v221, 0xffff0000, v213
	v_lshlrev_b32_e32 v94, 16, v86
	v_lshlrev_b32_e32 v192, 16, v184
	v_lshlrev_b32_e32 v222, 16, v214
	v_and_b32_e32 v95, 0xffff0000, v86
	v_and_b32_e32 v193, 0xffff0000, v184
	v_and_b32_e32 v223, 0xffff0000, v214
	v_lshlrev_b32_e32 v96, 16, v87
	v_lshlrev_b32_e32 v194, 16, v185
	v_lshlrev_b32_e32 v224, 16, v215
	v_and_b32_e32 v97, 0xffff0000, v87
	v_and_b32_e32 v195, 0xffff0000, v185
	v_and_b32_e32 v225, 0xffff0000, v215
	v_pk_add_f32 v[90:91], v[90:91], v[94:95]
	v_pk_add_f32 v[188:189], v[188:189], v[192:193]
	v_pk_add_f32 v[218:219], v[218:219], v[222:223]
	v_pk_add_f32 v[92:93], v[92:93], v[96:97]
	v_pk_add_f32 v[190:191], v[190:191], v[194:195]
	v_pk_add_f32 v[220:221], v[220:221], v[224:225]
	v_pk_mul_f32 v[98:99], v[90:91], v[90:91]
	v_pk_mul_f32 v[196:197], v[188:189], v[188:189]
	v_pk_mul_f32 v[226:227], v[218:219], v[218:219]
	v_pk_mul_f32 v[100:101], v[92:93], v[92:93]
	v_pk_mul_f32 v[198:199], v[190:191], v[190:191]
	v_pk_mul_f32 v[228:229], v[220:221], v[220:221]
	v_add_f32_e32 v110, v98, v99
	v_add_f32_e32 v208, v196, v197
	v_add_f32_e32 v238, v226, v227
	v_add_f32_e32 v110, v100, v110
	v_add_f32_e32 v208, v198, v208
	v_add_f32_e32 v238, v228, v238
	v_add_f32_e32 v110, v101, v110
	v_add_f32_e32 v208, v199, v208
	v_add_f32_e32 v238, v229, v238
	v_lshlrev_b32_e32 v102, 16, v88
	v_lshlrev_b32_e32 v200, 16, v186
	v_lshlrev_b32_e32 v230, 16, v216
	v_and_b32_e32 v103, 0xffff0000, v88
	v_and_b32_e32 v201, 0xffff0000, v186
	v_and_b32_e32 v231, 0xffff0000, v216
	v_add_f32_dpp v110, v110, v110 quad_perm:[1,0,3,2] row_mask:0xf bank_mask:0xf bound_ctrl:1
	v_add_f32_dpp v208, v208, v208 quad_perm:[1,0,3,2] row_mask:0xf bank_mask:0xf bound_ctrl:1
	v_add_f32_dpp v238, v238, v238 quad_perm:[1,0,3,2] row_mask:0xf bank_mask:0xf bound_ctrl:1
	v_add_f32_dpp v110, v110, v110 quad_perm:[2,3,0,1] row_mask:0xf bank_mask:0xf bound_ctrl:1
	v_add_f32_dpp v208, v208, v208 quad_perm:[2,3,0,1] row_mask:0xf bank_mask:0xf bound_ctrl:1
	v_add_f32_dpp v238, v238, v238 quad_perm:[2,3,0,1] row_mask:0xf bank_mask:0xf bound_ctrl:1
	v_add_f32_dpp v110, v110, v110 row_half_mirror row_mask:0xf bank_mask:0xf bound_ctrl:1
	v_add_f32_dpp v208, v208, v208 row_half_mirror row_mask:0xf bank_mask:0xf bound_ctrl:1
	v_add_f32_dpp v238, v238, v238 row_half_mirror row_mask:0xf bank_mask:0xf bound_ctrl:1
	v_add_f32_dpp v110, v110, v110 row_ror:8 row_mask:0xf bank_mask:0xf bound_ctrl:1
	v_add_f32_dpp v208, v208, v208 row_ror:8 row_mask:0xf bank_mask:0xf bound_ctrl:1
	v_add_f32_dpp v238, v238, v238 row_ror:8 row_mask:0xf bank_mask:0xf bound_ctrl:1
	v_fmamk_f32 v110, v110, 0x3c800000, v171
	v_fmamk_f32 v208, v208, 0x3c800000, v171
	v_fmamk_f32 v238, v238, 0x3c800000, v171
	v_rsq_f32_e32 v112, v110
	v_rsq_f32_e32 v210, v208
	v_rsq_f32_e32 v240, v238
	v_lshlrev_b32_e32 v104, 16, v89
	v_lshlrev_b32_e32 v202, 16, v187
	v_lshlrev_b32_e32 v232, 16, v217
	v_and_b32_e32 v105, 0xffff0000, v89
	v_and_b32_e32 v203, 0xffff0000, v187
	v_and_b32_e32 v233, 0xffff0000, v217
	v_mul_f32_e32 v106, 0xbfb8aa3b, v102
	v_mul_f32_e32 v204, 0xbfb8aa3b, v200
	v_mul_f32_e32 v234, 0xbfb8aa3b, v230
	v_mul_f32_e32 v107, 0xbfb8aa3b, v103
	v_mul_f32_e32 v205, 0xbfb8aa3b, v201
; __device__ __forceinline__ f32x4 unpk4(u32x2 v) { return (f32x4){bflo(v.x), bfhi(v.x), bflo(v.y), bfhi(v.y)}; }
; __device__ __forceinline__ u32x2 pk4(f32x4 v) { u32x2 r; r.x = pk2(v[0], v[1]); r.y = pk2(v[2], v[3]); return r; }
; __device__ __forceinline__ float siluf_(float x) { return x * rcpf_(1.f + __expf(-x)); }
; __device__ __forceinline__ int s5pos(int j) { if (j < CTX) return j; const int tok = j - CTX; return CTX + (tok & 63) * 128 + (tok >> 6); }
; __device__ __forceinline__ void phase_post(const PP& p, int l) {
;     ...
; #pragma unroll 3
;             for (int h = 0; h < 6; ++h) {
;                 const int c = h * 64 + 4 * c4;
;                 const f32x4 o = unpk4(*(const u32x2*)(YO + 2 * YS + (size_t)row * 384 + c)) + unpk4(*(const u32x2*)(YO + 3 * YS + (size_t)row * 384 + c));
;                 const float rs = __builtin_amdgcn_rsqf(red16(o[0] * o[0] + o[1] * o[1] + o[2] * o[2] + o[3] * o[3]) * (1.f / 64.f) + 1e-6f);
;                 f32x4 gt = unpk4(*(const u32x2*)(Z + (size_t)row * ZLD + 2584 + c));
; #pragma unroll
;                 for (int i = 0; i < 4; ++i) gt[i] = siluf_(gt[i]);
;                 *(u32x2*)(MIX + (size_t)row * DM + 384 + c) = pk4(o * rs * gn * gt);
;             }
;             const int n = s5pos(j), R = b * NCH + (n >> 5), t = n & 31;
;             const size_t GS5 = (size_t)GROWS * 512;
; #pragma unroll
;             for (int e = 0; e < 4; ++e) {
;                 const int ch = e * 64 + 4 * c4, nt = ch >> 4, hh = ch & 15;
;                 *(u32x2*)(MIX + (size_t)row * DM + 768 + ch) = *(const u32x2*)(Y5 + (size_t)(nt * 2) * GS5 + (size_t)R * 512 + t * 16 + hh);
;             }
	v_mul_f32_e32 v235, 0xbfb8aa3b, v231
	v_mul_f32_e32 v108, 0xbfb8aa3b, v104
	v_mul_f32_e32 v206, 0xbfb8aa3b, v202
	v_mul_f32_e32 v236, 0xbfb8aa3b, v232
	v_mul_f32_e32 v109, 0xbfb8aa3b, v105
	v_mul_f32_e32 v207, 0xbfb8aa3b, v203
	v_mul_f32_e32 v237, 0xbfb8aa3b, v233
	v_exp_f32_e32 v106, v106
	v_exp_f32_e32 v204, v204
	v_exp_f32_e32 v234, v234
	v_exp_f32_e32 v107, v107
	v_exp_f32_e32 v205, v205
	v_exp_f32_e32 v235, v235
	v_exp_f32_e32 v108, v108
	v_exp_f32_e32 v206, v206
	v_exp_f32_e32 v236, v236
	v_exp_f32_e32 v109, v109
	v_exp_f32_e32 v207, v207
	v_exp_f32_e32 v237, v237
	v_add_f32_e32 v106, 1.0, v106
	v_add_f32_e32 v204, 1.0, v204
	v_add_f32_e32 v234, 1.0, v234
	v_add_f32_e32 v107, 1.0, v107
	v_add_f32_e32 v205, 1.0, v205
	v_add_f32_e32 v235, 1.0, v235
	v_add_f32_e32 v108, 1.0, v108
	v_add_f32_e32 v206, 1.0, v206
	v_add_f32_e32 v236, 1.0, v236
	v_add_f32_e32 v109, 1.0, v109
	v_add_f32_e32 v207, 1.0, v207
	v_add_f32_e32 v237, 1.0, v237
	v_rcp_f32_e32 v106, v106
	v_rcp_f32_e32 v204, v204
	v_rcp_f32_e32 v234, v234
	v_rcp_f32_e32 v107, v107
	v_rcp_f32_e32 v205, v205
	v_rcp_f32_e32 v235, v235
	v_rcp_f32_e32 v108, v108
	v_rcp_f32_e32 v206, v206
	v_rcp_f32_e32 v236, v236
	v_rcp_f32_e32 v109, v109
	v_rcp_f32_e32 v207, v207
	v_rcp_f32_e32 v237, v237
	v_pk_mul_f32 v[90:91], v[90:91], v[112:113] op_sel_hi:[1,0]
	v_pk_mul_f32 v[188:189], v[188:189], v[210:211] op_sel_hi:[1,0]
	v_pk_mul_f32 v[218:219], v[218:219], v[240:241] op_sel_hi:[1,0]
	v_pk_mul_f32 v[92:93], v[92:93], v[112:113] op_sel_hi:[1,0]
	v_pk_mul_f32 v[190:191], v[190:191], v[210:211] op_sel_hi:[1,0]
	v_pk_mul_f32 v[220:221], v[220:221], v[240:241] op_sel_hi:[1,0]
	v_pk_mul_f32 v[102:103], v[106:107], v[102:103]
	v_pk_mul_f32 v[200:201], v[204:205], v[200:201]
	v_pk_mul_f32 v[230:231], v[234:235], v[230:231]
	v_pk_mul_f32 v[104:105], v[108:109], v[104:105]
	v_pk_mul_f32 v[202:203], v[206:207], v[202:203]
	v_pk_mul_f32 v[232:233], v[236:237], v[232:233]
	v_pk_mul_f32 v[90:91], v[2:3], v[90:91]
	v_pk_mul_f32 v[188:189], v[2:3], v[188:189]
	v_pk_mul_f32 v[218:219], v[2:3], v[218:219]
	v_pk_mul_f32 v[92:93], v[4:5], v[92:93]
	v_pk_mul_f32 v[190:191], v[4:5], v[190:191]
	v_pk_mul_f32 v[220:221], v[4:5], v[220:221]
	v_pk_mul_f32 v[90:91], v[102:103], v[90:91]
	v_pk_mul_f32 v[188:189], v[200:201], v[188:189]
	v_pk_mul_f32 v[218:219], v[230:231], v[218:219]
	v_pk_mul_f32 v[92:93], v[104:105], v[92:93]
	v_pk_mul_f32 v[190:191], v[202:203], v[190:191]
	v_pk_mul_f32 v[220:221], v[232:233], v[220:221]
	v_cvt_pk_bf16_f32 v90, v90, v91
	v_cvt_pk_bf16_f32 v188, v188, v189
	v_cvt_pk_bf16_f32 v218, v218, v219
	v_cvt_pk_bf16_f32 v91, v92, v93
	v_cvt_pk_bf16_f32 v189, v190, v191
	v_cvt_pk_bf16_f32 v219, v220, v221
	global_store_dwordx2 v[40:41], v[90:91], off offset:768
	global_store_dwordx2 v[40:41], v[188:189], off offset:896
	global_store_dwordx2 v[40:41], v[218:219], off offset:1024
	s_cmpk_eq_i32 s26, 0x300
	s_cbranch_scc0 .LBB0_1013
	v_lshl_add_u32 v2, s6, 2, v68
	v_mul_hi_i32 v3, v2, s30
	v_lshrrev_b32_e32 v4, 31, v3
	v_ashrrev_i32_e32 v3, 11, v3
	v_add_u32_e32 v8, v3, v4
	v_ashrrev_i32_e32 v3, 31, v2
	v_lshlrev_b64 v[4:5], 11, v[2:3]
	v_mad_i32_i24 v3, v8, s51, v2
	v_add_u32_e32 v9, 0xffffff00, v3
	v_lshlrev_b32_e32 v2, 7, v2
	v_and_b32_e32 v2, 0x1f80, v2
	v_lshrrev_b32_e32 v9, 6, v9
	v_cmp_gt_i32_e32 vcc, s33, v3
	v_add3_u32 v2, v2, v9, s33
	s_movk_i32 s7, 0x108
	v_cndmask_b32_e32 v9, v2, v3, vcc
	v_ashrrev_i32_e32 v2, 5, v9
	v_mad_i32_i24 v2, v8, s7, v2
	v_ashrrev_i32_e32 v3, 31, v2
	v_lshlrev_b64 v[2:3], 10, v[2:3]
	v_lshlrev_b32_e32 v8, 5, v9
	v_lshl_add_u64 v[2:3], s[18:19], 0, v[2:3]
	v_and_b32_e32 v8, 0x3e0, v8
	v_mov_b32_e32 v9, v0
	v_lshl_add_u64 v[2:3], v[2:3], 0, v[8:9]
	v_mov_b32_e32 v25, v0
	v_lshl_add_u64 v[2:3], v[2:3], 0, v[24:25]
	v_mov_b32_e32 v27, v0
	v_lshl_add_u64 v[84:85], v[2:3], 0, v[26:27]
	v_mov_b32_e32 v29, v0
	v_mov_b32_e32 v31, v0
	v_mov_b32_e32 v33, v0
	v_lshl_add_u64 v[86:87], v[2:3], 0, v[28:29]
	v_lshl_add_u64 v[88:89], v[2:3], 0, v[30:31]
	v_lshl_add_u64 v[90:91], v[2:3], 0, v[32:33]
	global_load_dwordx2 v[92:93], v[84:85], off
	global_load_dwordx2 v[94:95], v[86:87], off
	global_load_dwordx2 v[96:97], v[88:89], off
	global_load_dwordx2 v[98:99], v[90:91], off
	v_lshl_add_u64 v[4:5], s[10:11], 0, v[4:5]
	v_lshlrev_b32_e32 v10, 1, v14
	v_mov_b32_e32 v11, v0
	v_lshl_add_u64 v[4:5], v[4:5], 0, v[10:11]
	s_add_i32 s6, s6, 1
	v_add_u32_e32 v34, 4, v34
	s_waitcnt vmcnt(0)
	global_store_dwordx2 v[4:5], v[92:93], off offset:1536
	global_store_dwordx2 v[4:5], v[94:95], off offset:1664
	global_store_dwordx2 v[4:5], v[96:97], off offset:1792
	global_store_dwordx2 v[4:5], v[98:99], off offset:1920
	s_cmp_eq_u32 s6, 4
	s_cbranch_scc0 .LBB0_1012
